# GLA pass-1 item: k/gate/v/up-proj/bias loads issued together (were three serialized load-wait groups)
# speedup vs baseline: 1.0191x; 1.0014x over previous
; DI float lo_f(unsigned w) { return __uint_as_float(w << 16); }
; DI float hi_f(unsigned w) { return __uint_as_float(w & 0xffff0000u); }
; DI void gla_load(const bf16_t* P, const float* wa2  , const float* ba  , float* L, int cid, int hh) {
;     ...
;     {
;         const int r = tid >> 3, d0 = (tid & 7) * 4;
;         const bf16_t* rp = P + (row0 + r) * IN_DIM;
;         const u32x2 kv = *(const u32x2*)(rp + C_GK + hh * 32 + d0), gv = *(const u32x2*)(rp + C_GLR + d0);
;         L[GL_K + r * 33 + d0] = lo_f(kv[0]); L[GL_K + r * 33 + d0 + 1] = hi_f(kv[0]); L[GL_K + r * 33 + d0 + 2] = lo_f(kv[1]); L[GL_K + r * 33 + d0 + 3] = hi_f(kv[1]);
;         L[GL_G + r * 33 + d0] = lo_f(gv[0]); L[GL_G + r * 33 + d0 + 1] = hi_f(gv[0]); L[GL_G + r * 33 + d0 + 2] = lo_f(gv[1]); L[GL_G + r * 33 + d0 + 3] = hi_f(gv[1]);
;         const int e0 = (tid & 7) * 8;
;         const u32x4 vv = *(const u32x4*)(rp + C_GV + hh * 64 + e0);
;         {
;             const int idx = tid * 2, wd = idx >> 9, wr_ = (idx >> 5) & 15, wdd = idx & 31;
;             const f32x2 wv2 = *(const f32x2*)(wa2 + (wd * 16 + wr_) * 128 + hh * 32 + wdd);
;             *(f32x2*)(L + GL_S + idx) = wv2;
;             if (tid < 64) L[GL_S + 1024 + tid] = ba[(tid >> 5) * 128 + hh * 32 + (tid & 31)];
;         }
;         *(u32x4*)((bf16_t*)((unsigned char*)L + G3_VT) + r * 72 + e0) = vv;
;     }
;     __syncthreads();
;     {
;         const int r = tid >> 3, d0 = (tid & 7) * 4;
; #pragma unroll
;         for (int dir = 0; dir < 2; ++dir) {
;             f32x4 z = *(const f32x4*)(L + GL_S + 1024 + dir * 32 + d0);
; #pragma unroll
;             for (int rr = 0; rr < 16; ++rr) {
;                 const float gl = L[GL_G + r * 33 + dir * 16 + rr];
;                 const f32x4 w = *(const f32x4*)(L + GL_S + (dir * 16 + rr) * 32 + d0);
;                 z[0] += gl * w[0]; z[1] += gl * w[1]; z[2] += gl * w[2]; z[3] += gl * w[3];
.LBB0_462:
	s_and_b64 vcc, exec, s[18:19]
	s_cbranch_vccz .LBB0_500
	s_load_dwordx2 s[4:5], s[0:1], 0x70
	v_mov_b32_e32 v11, v176
	s_load_dwordx2 s[40:41], s[0:1], 0x78
	v_mov_b64_e32 v[4:5], s[76:77]
	s_waitcnt lgkmcnt(0)
	s_add_u32 s42, s4, s14
	s_addc_u32 s43, s5, s15
	s_ashr_i32 s18, s2, 2
	s_ashr_i32 s19, s18, 31
	v_ashrrev_i32_e32 v6, 3, v11
	s_lshl_b64 s[4:5], s[18:19], 6
	v_ashrrev_i32_e32 v7, 31, v6
	v_lshl_add_u64 v[2:3], s[4:5], 0, v[6:7]
	s_and_b32 s2, s34, 3
	v_mad_u64_u32 v[4:5], s[4:5], v2, s28, v[4:5]
	v_and_b32_e32 v8, 7, v11
	v_mad_i32_i24 v5, v3, s28, v5
	s_lshl_b32 s72, s2, 6
	v_lshl_add_u64 v[2:3], v[4:5], 0, s[72:73]
	v_lshlrev_b32_e32 v0, 3, v8
	v_lshl_add_u64 v[2:3], v[2:3], 0, v[0:1]
	s_barrier
	global_load_dwordx2 v[40:41], v[2:3], off offset:2304
	v_lshl_add_u64 v[12:13], v[4:5], 0, v[0:1]
	global_load_dwordx2 v[42:43], v[12:13], off offset:3584
	v_mul_lo_u32 v7, v6, s86
	v_add_u32_e32 v7, 0, v7
	v_lshlrev_b32_e32 v16, 4, v8
	v_add_u32_e32 v12, v7, v16
	s_mov_b32 s3, 0x1fffff0
	s_lshl_b32 s72, s2, 7
	v_mov_b32_e32 v17, v1
	v_cmp_gt_i32_e32 vcc, 64, v11
	v_lshlrev_b32_e32 v13, 2, v11
	v_bfe_u32 v9, v11, 4, 4
	v_ashrrev_i32_e32 v10, 4, v11
	v_and_or_b32 v9, v10, s3, v9
	v_lshlrev_b32_e32 v14, 7, v9
	v_ashrrev_i32_e32 v15, 31, v14
	v_lshl_add_u64 v[2:3], v[4:5], 0, s[72:73]
	v_lshl_add_u64 v[14:15], v[14:15], 2, s[42:43]
	v_lshlrev_b32_e32 v9, 3, v11
	v_lshl_add_u64 v[2:3], v[2:3], 0, v[16:17]
	v_lshl_add_u64 v[14:15], v[14:15], 0, s[72:73]
	v_and_b32_e32 v16, 0x78, v9
	v_lshl_add_u64 v[14:15], v[14:15], 0, v[16:17]
	global_load_dwordx4 v[44:47], v[2:3], off offset:2560
	global_load_dwordx2 v[48:49], v[14:15], off
	v_add_u32_e32 v9, 0, v9
	v_add_u32_e32 v51, 0x16f00, v9
	s_and_saveexec_b64 s[20:21], vcc
	s_cbranch_execz .Lgla1_noba
	s_lshl_b32 s3, s2, 5
	v_and_b32_e32 v9, 0xffffff80, v13
	v_and_b32_e32 v14, 31, v11
	s_add_u32 s4, s40, s12
	v_or3_b32 v14, v14, v9, s3
	s_addc_u32 s5, s41, s13
	v_ashrrev_i32_e32 v15, 31, v14
	v_lshl_add_u64 v[14:15], v[14:15], 2, s[4:5]
	global_load_dword v50, v[14:15], off
.Lgla1_noba:
	s_or_b64 exec, exec, s[20:21]
	v_add_u32_e32 v52, 0x2100, v12
	s_waitcnt vmcnt(0)
	v_lshlrev_b32_e32 v9, 16, v40
	v_and_b32_e32 v2, 0xffff0000, v40
	ds_write2_b32 v52, v9, v2 offset1:1
	v_lshlrev_b32_e32 v2, 16, v41
	v_add_u32_e32 v9, 0x2108, v12
	v_and_b32_e32 v3, 0xffff0000, v41
	ds_write2_b32 v9, v2, v3 offset1:1
	v_lshlrev_b32_e32 v2, 16, v42
	v_add_u32_e32 v3, 0x8600, v12
	v_and_b32_e32 v9, 0xffff0000, v42
	ds_write2_b32 v3, v2, v9 offset1:1
	v_lshlrev_b32_e32 v2, 16, v43
	v_add_u32_e32 v3, 0x8608, v12
	v_and_b32_e32 v9, 0xffff0000, v43
	ds_write2_b32 v3, v2, v9 offset1:1
	ds_write_b64 v51, v[48:49]
	s_and_saveexec_b64 s[20:21], vcc
	v_lshl_add_u32 v14, v11, 2, 0
	v_add_u32_e32 v14, 0x17f00, v14
	ds_write_b32 v14, v50
	s_or_b64 exec, exec, s[20:21]
	v_mul_lo_u32 v6, v6, s62
	v_lshlrev_b32_e32 v0, 1, v0
	v_lshlrev_b32_e32 v8, 2, v8
	v_add3_u32 v0, s69, v6, v0
	ds_write_b128 v0, v[44:47]
	v_lshl_add_u32 v0, v8, 2, 0
	v_add_u32_e32 v6, 0x17f00, v0
	v_add_u32_e32 v8, 0x8600, v7
	s_waitcnt lgkmcnt(0)
	s_barrier
	v_add_u32_e32 v0, 0x16f00, v0
	ds_read_b128 v[2:5], v6
	ds_read2_b32 v[8:9], v8 offset1:1
	ds_read_b128 v[14:17], v0
	s_mov_b32 s3, 0xbfb8aa3b
	s_mov_b32 s4, 0x3f317217
	s_mov_b32 s5, 0x7f800000
	s_mov_b32 s6, 0x3d800000
	s_waitcnt lgkmcnt(0)
	v_fma_f32 v22, v8, v14, v2
	v_fma_f32 v23, v8, v15, v3
	v_fma_f32 v4, v8, v16, v4
	v_fmac_f32_e32 v5, v8, v17
	ds_read_b128 v[14:17], v0 offset:128
	v_add_u32_e32 v2, 0x8608, v7
	s_lshl_b64 s[18:19], s[18:19], 2
	s_or_b32 s18, s18, s2
	v_readlane_b32 s2, v255, 20
	s_waitcnt lgkmcnt(0)
	v_fmac_f32_e32 v22, v9, v14
	v_fmac_f32_e32 v23, v9, v15
	v_fmac_f32_e32 v4, v9, v16
	v_fmac_f32_e32 v5, v9, v17
	ds_read2_b32 v[2:3], v2 offset1:1
	ds_read_b128 v[14:17], v0 offset:256
	s_waitcnt lgkmcnt(0)
	v_fmac_f32_e32 v22, v2, v14
	v_fmac_f32_e32 v23, v2, v15
	v_fmac_f32_e32 v4, v2, v16
	v_fmac_f32_e32 v5, v2, v17
	ds_read_b128 v[14:17], v0 offset:384
	v_add_u32_e32 v2, 0x8610, v7
	s_waitcnt lgkmcnt(0)
	v_fmac_f32_e32 v22, v3, v14
	v_fmac_f32_e32 v23, v3, v15
	v_fmac_f32_e32 v4, v3, v16
	v_fmac_f32_e32 v5, v3, v17
	ds_read2_b32 v[2:3], v2 offset1:1
	ds_read_b128 v[14:17], v0 offset:512
	s_waitcnt lgkmcnt(0)
	v_fmac_f32_e32 v22, v2, v14
	v_fmac_f32_e32 v23, v2, v15
	v_fmac_f32_e32 v4, v2, v16
	v_fmac_f32_e32 v5, v2, v17
	ds_read_b128 v[14:17], v0 offset:640
	v_add_u32_e32 v2, 0x8618, v7
	s_waitcnt lgkmcnt(0)
	v_fmac_f32_e32 v22, v3, v14
	v_fmac_f32_e32 v23, v3, v15
	v_fmac_f32_e32 v4, v3, v16
	v_fmac_f32_e32 v5, v3, v17
	ds_read_b128 v[14:17], v0 offset:768
	ds_read_b128 v[18:21], v0 offset:896
	ds_read2_b32 v[2:3], v2 offset1:1
	s_waitcnt lgkmcnt(2)
	v_mov_b32_e32 v8, v15
	s_waitcnt lgkmcnt(1)
	v_mov_b32_e32 v9, v19
	s_waitcnt lgkmcnt(0)
	v_pk_mul_f32 v[8:9], v[2:3], v[8:9]
	v_mov_b32_e32 v15, v18
	v_add_f32_e32 v8, v23, v8
	v_add_f32_e32 v23, v8, v9
	v_mov_b32_e32 v8, v16
	v_mov_b32_e32 v9, v20
	v_mov_b32_e32 v20, v17
	v_pk_mul_f32 v[14:15], v[2:3], v[14:15]
	v_pk_mul_f32 v[8:9], v[2:3], v[8:9]
	v_pk_mul_f32 v[2:3], v[2:3], v[20:21]
	v_add_f32_e32 v14, v22, v14
	v_add_f32_e32 v4, v4, v8
	v_add_f32_e32 v2, v5, v2
	v_add_u32_e32 v8, 0x8620, v7
	v_add_f32_e32 v22, v14, v15
	v_add_f32_e32 v24, v4, v9
	v_add_f32_e32 v20, v2, v3
	ds_read_b128 v[2:5], v0 offset:1024
	ds_read_b128 v[14:17], v0 offset:1152
	ds_read2_b32 v[8:9], v8 offset1:1
	s_waitcnt lgkmcnt(2)
	v_mov_b32_e32 v18, v3
	s_waitcnt lgkmcnt(1)
	v_mov_b32_e32 v3, v14
	s_waitcnt lgkmcnt(0)
; DI void gla_load(const bf16_t* P, const float* wa2  , const float* ba  , float* L, int cid, int hh) {
;     ...
;         for (int dir = 0; dir < 2; ++dir) {
;             f32x4 z = *(const f32x4*)(L + GL_S + 1024 + dir * 32 + d0);
; #pragma unroll
;             for (int rr = 0; rr < 16; ++rr) {
;                 const float gl = L[GL_G + r * 33 + dir * 16 + rr];
;                 const f32x4 w = *(const f32x4*)(L + GL_S + (dir * 16 + rr) * 32 + d0);
;                 z[0] += gl * w[0]; z[1] += gl * w[1]; z[2] += gl * w[2]; z[3] += gl * w[3];
;             }
; #pragma unroll
;             for (int j = 0; j < 4; ++j) {
;                 const float zz = z[j];
;                 const float ls = fminf(zz, 0.f) - __logf(1.f + __expf(-fabsf(zz)));
;                 L[(dir ? GL_BB : GL_BF) + r * 33 + d0 + j] = ls * (1.f / 16.f);
;             }
;         }
	v_pk_mul_f32 v[2:3], v[8:9], v[2:3]
	v_mov_b32_e32 v19, v15
	v_add_f32_e32 v2, v22, v2
	v_add_f32_e32 v21, v2, v3
	v_mov_b32_e32 v2, v4
	v_mov_b32_e32 v3, v16
	v_pk_mul_f32 v[2:3], v[8:9], v[2:3]
	v_pk_mul_f32 v[18:19], v[8:9], v[18:19]
	v_add_f32_e32 v2, v24, v2
	v_mov_b32_e32 v16, v5
	v_add_f32_e32 v15, v23, v18
	v_add_f32_e32 v23, v2, v3
	v_pk_mul_f32 v[2:3], v[8:9], v[16:17]
	v_add_u32_e32 v8, 0x8628, v7
	v_add_f32_e32 v2, v20, v2
	v_add_f32_e32 v22, v15, v19
	v_add_f32_e32 v20, v2, v3
	ds_read_b128 v[2:5], v0 offset:1280
	ds_read_b128 v[14:17], v0 offset:1408
	ds_read2_b32 v[8:9], v8 offset1:1
	s_waitcnt lgkmcnt(2)
	v_mov_b32_e32 v18, v3
	s_waitcnt lgkmcnt(1)
	v_mov_b32_e32 v3, v14
	s_waitcnt lgkmcnt(0)
	v_pk_mul_f32 v[2:3], v[8:9], v[2:3]
	v_mov_b32_e32 v19, v15
	v_add_f32_e32 v2, v21, v2
	v_add_f32_e32 v21, v2, v3
	v_mov_b32_e32 v2, v4
	v_mov_b32_e32 v3, v16
	v_pk_mul_f32 v[2:3], v[8:9], v[2:3]
	v_mov_b32_e32 v16, v5
	v_add_f32_e32 v2, v23, v2
	v_pk_mul_f32 v[18:19], v[8:9], v[18:19]
	v_add_f32_e32 v23, v2, v3
	v_pk_mul_f32 v[2:3], v[8:9], v[16:17]
	v_add_f32_e32 v15, v22, v18
	v_add_f32_e32 v2, v20, v2
	v_add_u32_e32 v8, 0x8630, v7
	v_add_f32_e32 v22, v15, v19
	v_add_f32_e32 v20, v2, v3
	ds_read_b128 v[2:5], v0 offset:1536
	ds_read_b128 v[14:17], v0 offset:1664
	ds_read2_b32 v[8:9], v8 offset1:1
	s_waitcnt lgkmcnt(2)
	v_mov_b32_e32 v18, v3
	s_waitcnt lgkmcnt(1)
	v_mov_b32_e32 v3, v14
	s_waitcnt lgkmcnt(0)
	v_pk_mul_f32 v[2:3], v[8:9], v[2:3]
	v_mov_b32_e32 v19, v15
	v_add_f32_e32 v2, v21, v2
	v_add_f32_e32 v21, v2, v3
	v_mov_b32_e32 v2, v4
	v_mov_b32_e32 v3, v16
	v_pk_mul_f32 v[2:3], v[8:9], v[2:3]
	v_mov_b32_e32 v16, v5
	v_add_f32_e32 v2, v23, v2
	v_pk_mul_f32 v[18:19], v[8:9], v[18:19]
	v_add_f32_e32 v23, v2, v3
	v_pk_mul_f32 v[2:3], v[8:9], v[16:17]
	v_add_f32_e32 v15, v22, v18
	v_add_f32_e32 v2, v20, v2
	v_add_u32_e32 v8, 0x8638, v7
	v_add_f32_e32 v22, v15, v19
	v_add_f32_e32 v20, v2, v3
	ds_read_b128 v[2:5], v0 offset:1792
	ds_read_b128 v[14:17], v0 offset:1920
	ds_read2_b32 v[8:9], v8 offset1:1
	s_waitcnt lgkmcnt(2)
	v_mov_b32_e32 v18, v3
	s_waitcnt lgkmcnt(1)
	v_mov_b32_e32 v3, v14
	s_waitcnt lgkmcnt(0)
	v_pk_mul_f32 v[2:3], v[8:9], v[2:3]
	v_mov_b32_e32 v19, v15
	v_add_f32_e32 v2, v21, v2
	v_add_f32_e32 v14, v2, v3
	v_mov_b32_e32 v2, v4
	v_mov_b32_e32 v3, v16
	v_pk_mul_f32 v[2:3], v[8:9], v[2:3]
	v_pk_mul_f32 v[18:19], v[8:9], v[18:19]
	v_add_f32_e32 v2, v23, v2
	v_mov_b32_e32 v16, v5
	v_add_f32_e32 v15, v22, v18
	v_add_f32_e32 v18, v2, v3
	v_pk_mul_f32 v[2:3], v[8:9], v[16:17]
	v_add_f32_e32 v15, v15, v19
	v_add_f32_e32 v2, v20, v2
	v_add_f32_e32 v8, v2, v3
	v_mul_f32_e64 v3, |v14|, s3
	v_exp_f32_e32 v3, v3
	v_mul_f32_e64 v5, |v15|, s3
	v_exp_f32_e32 v5, v5
	v_min_f32_e32 v2, 0, v14
	v_add_f32_e32 v3, 1.0, v3
	v_cmp_gt_f32_e32 vcc, s60, v3
	v_add_f32_e32 v5, 1.0, v5
	v_add_u32_e32 v9, 0xa700, v12
	v_cndmask_b32_e64 v4, 0, 32, vcc
	v_ldexp_f32 v3, v3, v4
	v_log_f32_e32 v3, v3
	s_nop 0
	v_mul_f32_e32 v4, 0x3f317217, v3
	v_fma_f32 v4, v3, s4, -v4
	v_fmac_f32_e32 v4, 0x3377d1cf, v3
	v_fmac_f32_e32 v4, 0x3f317217, v3
	v_cmp_lt_f32_e64 s[40:41], |v3|, s5
	s_nop 1
	v_cndmask_b32_e64 v3, v3, v4, s[40:41]
	v_cndmask_b32_e32 v4, 0, v183, vcc
	v_cmp_gt_f32_e32 vcc, s60, v5
	v_sub_f32_e32 v4, v3, v4
	v_min_f32_e32 v3, 0, v15
	v_cndmask_b32_e64 v14, 0, 32, vcc
	v_ldexp_f32 v5, v5, v14
	v_log_f32_e32 v5, v5
	s_nop 0
	v_mul_f32_e32 v14, 0x3f317217, v5
	v_fma_f32 v14, v5, s4, -v14
	v_fmac_f32_e32 v14, 0x3377d1cf, v5
	v_fmac_f32_e32 v14, 0x3f317217, v5
	v_cmp_lt_f32_e64 s[40:41], |v5|, s5
	s_nop 1
	v_cndmask_b32_e64 v5, v5, v14, s[40:41]
	v_cndmask_b32_e32 v14, 0, v183, vcc
	v_sub_f32_e32 v5, v5, v14
	v_pk_add_f32 v[2:3], v[2:3], v[4:5] neg_lo:[0,1] neg_hi:[0,1]
	v_mul_f32_e64 v5, |v8|, s3
	v_pk_mul_f32 v[2:3], v[2:3], s[6:7] op_sel_hi:[1,0]
	ds_write2_b32 v9, v2, v3 offset1:1
	v_mul_f32_e64 v3, |v18|, s3
	v_exp_f32_e32 v3, v3
	v_exp_f32_e32 v5, v5
	v_min_f32_e32 v2, 0, v18
	v_add_u32_e32 v9, 0xa708, v12
	v_add_f32_e32 v3, 1.0, v3
	v_cmp_gt_f32_e32 vcc, s60, v3
	v_add_f32_e32 v5, 1.0, v5
	s_nop 0
	v_cndmask_b32_e64 v4, 0, 32, vcc
	v_ldexp_f32 v3, v3, v4
	v_log_f32_e32 v3, v3
	s_nop 0
	v_mul_f32_e32 v4, 0x3f317217, v3
	v_fma_f32 v4, v3, s4, -v4
	v_fmac_f32_e32 v4, 0x3377d1cf, v3
	v_fmac_f32_e32 v4, 0x3f317217, v3
	v_cmp_lt_f32_e64 s[40:41], |v3|, s5
	s_nop 1
	v_cndmask_b32_e64 v3, v3, v4, s[40:41]
	v_cndmask_b32_e32 v4, 0, v183, vcc
	v_cmp_gt_f32_e32 vcc, s60, v5
	v_sub_f32_e32 v4, v3, v4
	v_min_f32_e32 v3, 0, v8
	v_cndmask_b32_e64 v8, 0, 32, vcc
	v_ldexp_f32 v5, v5, v8
	v_log_f32_e32 v5, v5
	s_nop 0
	v_mul_f32_e32 v8, 0x3f317217, v5
	v_fma_f32 v8, v5, s4, -v8
	v_fmac_f32_e32 v8, 0x3377d1cf, v5
	v_fmac_f32_e32 v8, 0x3f317217, v5
	v_cmp_lt_f32_e64 s[40:41], |v5|, s5
	s_nop 1
	v_cndmask_b32_e64 v5, v5, v8, s[40:41]
	v_cndmask_b32_e32 v8, 0, v183, vcc
	v_sub_f32_e32 v5, v5, v8
	v_pk_add_f32 v[2:3], v[2:3], v[4:5] neg_lo:[0,1] neg_hi:[0,1]
	s_nop 0
	v_pk_mul_f32 v[2:3], v[2:3], s[6:7] op_sel_hi:[1,0]
	ds_write2_b32 v9, v2, v3 offset1:1
	ds_read_b128 v[2:5], v6 offset:128
	v_add_u32_e32 v6, 0x8640, v7
	ds_read2_b32 v[8:9], v6 offset1:1
	ds_read_b128 v[14:17], v0 offset:2048
	s_waitcnt lgkmcnt(0)
	v_fma_f32 v6, v8, v14, v2
	v_fma_f32 v3, v8, v15, v3
	v_fma_f32 v2, v8, v16, v4
	v_fmac_f32_e32 v5, v8, v17
	ds_read_b128 v[14:17], v0 offset:2176
	v_add_u32_e32 v4, 0x8648, v7
	s_waitcnt lgkmcnt(0)
	v_fmac_f32_e32 v6, v9, v14
	v_fmac_f32_e32 v3, v9, v15
	v_fmac_f32_e32 v2, v9, v16
	v_fmac_f32_e32 v5, v9, v17
	ds_read2_b32 v[8:9], v4 offset1:1
	ds_read_b128 v[14:17], v0 offset:2304
	v_add_u32_e32 v4, 0x8650, v7
	s_waitcnt lgkmcnt(0)
; DI void gla_load(const bf16_t* P, const float* wa2  , const float* ba  , float* L, int cid, int hh) {
;     ...
;         for (int dir = 0; dir < 2; ++dir) {
;             f32x4 z = *(const f32x4*)(L + GL_S + 1024 + dir * 32 + d0);
; #pragma unroll
;             for (int rr = 0; rr < 16; ++rr) {
;                 const float gl = L[GL_G + r * 33 + dir * 16 + rr];
;                 const f32x4 w = *(const f32x4*)(L + GL_S + (dir * 16 + rr) * 32 + d0);
;                 z[0] += gl * w[0]; z[1] += gl * w[1]; z[2] += gl * w[2]; z[3] += gl * w[3];
;             }
; #pragma unroll
;             for (int j = 0; j < 4; ++j) {
;                 const float zz = z[j];
;                 const float ls = fminf(zz, 0.f) - __logf(1.f + __expf(-fabsf(zz)));
;                 L[(dir ? GL_BB : GL_BF) + r * 33 + d0 + j] = ls * (1.f / 16.f);
;             }
;         }
;     }
;     __syncthreads();
	v_fmac_f32_e32 v6, v8, v14
	v_fmac_f32_e32 v3, v8, v15
	v_fmac_f32_e32 v2, v8, v16
	v_fmac_f32_e32 v5, v8, v17
	ds_read_b128 v[14:17], v0 offset:2432
	s_waitcnt lgkmcnt(0)
	v_fmac_f32_e32 v6, v9, v14
	v_fmac_f32_e32 v3, v9, v15
	v_fmac_f32_e32 v2, v9, v16
	v_fmac_f32_e32 v5, v9, v17
	ds_read2_b32 v[8:9], v4 offset1:1
	ds_read_b128 v[14:17], v0 offset:2560
	v_add_u32_e32 v4, 0x8658, v7
	s_waitcnt lgkmcnt(0)
	v_fmac_f32_e32 v6, v8, v14
	v_fmac_f32_e32 v3, v8, v15
	v_fmac_f32_e32 v2, v8, v16
	v_fmac_f32_e32 v5, v8, v17
	ds_read_b128 v[14:17], v0 offset:2688
	s_waitcnt lgkmcnt(0)
	v_fmac_f32_e32 v6, v9, v14
	v_fmac_f32_e32 v3, v9, v15
	v_fmac_f32_e32 v2, v9, v16
	v_fmac_f32_e32 v5, v9, v17
	ds_read_b128 v[14:17], v0 offset:2816
	ds_read_b128 v[18:21], v0 offset:2944
	ds_read2_b32 v[8:9], v4 offset1:1
	s_waitcnt lgkmcnt(2)
	v_mov_b32_e32 v22, v15
	s_waitcnt lgkmcnt(1)
	v_mov_b32_e32 v15, v18
	s_waitcnt lgkmcnt(0)
	v_pk_mul_f32 v[14:15], v[8:9], v[14:15]
	v_mov_b32_e32 v23, v19
	v_add_f32_e32 v4, v6, v14
	v_add_f32_e32 v6, v4, v15
	v_mov_b32_e32 v14, v16
	v_mov_b32_e32 v15, v20
	v_pk_mul_f32 v[22:23], v[8:9], v[22:23]
	v_pk_mul_f32 v[14:15], v[8:9], v[14:15]
	v_add_f32_e32 v3, v3, v22
	v_add_f32_e32 v2, v2, v14
	v_mov_b32_e32 v20, v17
	v_add_f32_e32 v22, v3, v23
	v_add_f32_e32 v23, v2, v15
	v_pk_mul_f32 v[2:3], v[8:9], v[20:21]
	v_add_u32_e32 v8, 0x8660, v7
	v_add_f32_e32 v2, v5, v2
	v_add_f32_e32 v20, v2, v3
	ds_read_b128 v[2:5], v0 offset:3072
	ds_read_b128 v[14:17], v0 offset:3200
	ds_read2_b32 v[8:9], v8 offset1:1
	s_waitcnt lgkmcnt(2)
	v_mov_b32_e32 v18, v3
	s_waitcnt lgkmcnt(1)
	v_mov_b32_e32 v3, v14
	s_waitcnt lgkmcnt(0)
	v_pk_mul_f32 v[2:3], v[8:9], v[2:3]
	v_mov_b32_e32 v19, v15
	v_add_f32_e32 v2, v6, v2
	v_add_f32_e32 v6, v2, v3
	v_mov_b32_e32 v2, v4
	v_mov_b32_e32 v3, v16
	v_pk_mul_f32 v[2:3], v[8:9], v[2:3]
	v_pk_mul_f32 v[18:19], v[8:9], v[18:19]
	v_add_f32_e32 v2, v23, v2
	v_mov_b32_e32 v16, v5
	v_add_f32_e32 v15, v22, v18
	v_add_f32_e32 v22, v2, v3
	v_pk_mul_f32 v[2:3], v[8:9], v[16:17]
	v_add_u32_e32 v8, 0x8668, v7
	v_add_f32_e32 v2, v20, v2
	v_add_f32_e32 v21, v15, v19
	v_add_f32_e32 v20, v2, v3
	ds_read_b128 v[2:5], v0 offset:3328
	ds_read_b128 v[14:17], v0 offset:3456
	ds_read2_b32 v[8:9], v8 offset1:1
	s_waitcnt lgkmcnt(2)
	v_mov_b32_e32 v18, v3
	s_waitcnt lgkmcnt(1)
	v_mov_b32_e32 v3, v14
	s_waitcnt lgkmcnt(0)
	v_pk_mul_f32 v[2:3], v[8:9], v[2:3]
	v_mov_b32_e32 v19, v15
	v_add_f32_e32 v2, v6, v2
	v_add_f32_e32 v6, v2, v3
	v_mov_b32_e32 v2, v4
	v_mov_b32_e32 v3, v16
	v_pk_mul_f32 v[2:3], v[8:9], v[2:3]
	v_mov_b32_e32 v16, v5
	v_add_f32_e32 v2, v22, v2
	v_pk_mul_f32 v[18:19], v[8:9], v[18:19]
	v_add_f32_e32 v22, v2, v3
	v_pk_mul_f32 v[2:3], v[8:9], v[16:17]
	v_add_f32_e32 v15, v21, v18
	v_add_f32_e32 v2, v20, v2
	v_add_u32_e32 v8, 0x8670, v7
	v_add_f32_e32 v21, v15, v19
	v_add_f32_e32 v20, v2, v3
	ds_read_b128 v[2:5], v0 offset:3584
	ds_read_b128 v[16:19], v0 offset:3712
	ds_read2_b32 v[8:9], v8 offset1:1
	s_waitcnt lgkmcnt(2)
	v_mov_b32_e32 v14, v3
	s_waitcnt lgkmcnt(1)
	v_mov_b32_e32 v3, v16
	s_waitcnt lgkmcnt(0)
	v_pk_mul_f32 v[2:3], v[8:9], v[2:3]
	v_mov_b32_e32 v15, v17
	v_add_f32_e32 v2, v6, v2
	v_add_f32_e32 v16, v2, v3
	v_mov_b32_e32 v2, v4
	v_mov_b32_e32 v3, v18
	v_pk_mul_f32 v[14:15], v[8:9], v[14:15]
	v_pk_mul_f32 v[2:3], v[8:9], v[2:3]
	v_add_f32_e32 v14, v21, v14
	v_add_f32_e32 v2, v22, v2
	v_mov_b32_e32 v18, v5
	v_add_f32_e32 v17, v14, v15
	v_add_f32_e32 v14, v2, v3
	v_pk_mul_f32 v[2:3], v[8:9], v[18:19]
	v_add_u32_e32 v18, 0x8678, v7
	v_add_f32_e32 v2, v20, v2
	v_add_f32_e32 v15, v2, v3
	ds_read_b128 v[2:5], v0 offset:3840
	ds_read_b128 v[6:9], v0 offset:3968
	ds_read2_b32 v[18:19], v18 offset1:1
	s_waitcnt lgkmcnt(2)
	v_mov_b32_e32 v20, v3
	s_waitcnt lgkmcnt(1)
	v_mov_b32_e32 v3, v6
	s_waitcnt lgkmcnt(0)
	v_pk_mul_f32 v[2:3], v[18:19], v[2:3]
	v_mov_b32_e32 v21, v7
	v_add_f32_e32 v2, v16, v2
	v_add_f32_e32 v6, v2, v3
	v_mov_b32_e32 v2, v4
	v_mov_b32_e32 v3, v8
	v_pk_mul_f32 v[2:3], v[18:19], v[2:3]
	v_mov_b32_e32 v8, v5
	v_add_f32_e32 v2, v14, v2
	v_add_f32_e32 v7, v2, v3
	v_pk_mul_f32 v[2:3], v[18:19], v[8:9]
	v_pk_mul_f32 v[20:21], v[18:19], v[20:21]
	v_add_f32_e32 v2, v15, v2
	v_add_f32_e32 v8, v2, v3
	v_mul_f32_e64 v3, |v6|, s3
	v_exp_f32_e32 v3, v3
	v_add_f32_e32 v0, v17, v20
	v_add_f32_e32 v0, v0, v21
	v_min_f32_e32 v2, 0, v6
	v_add_f32_e32 v3, 1.0, v3
	v_cmp_gt_f32_e32 vcc, s60, v3
	v_add_u32_e32 v9, 0xc800, v12
	s_nop 0
	v_cndmask_b32_e64 v4, 0, 32, vcc
	v_ldexp_f32 v3, v3, v4
	v_log_f32_e32 v3, v3
	s_nop 0
	v_mul_f32_e32 v4, 0x3f317217, v3
	v_fma_f32 v4, v3, s4, -v4
	v_fmac_f32_e32 v4, 0x3377d1cf, v3
	v_fmac_f32_e32 v4, 0x3f317217, v3
	v_cmp_lt_f32_e64 s[40:41], |v3|, s5
	s_nop 1
	v_cndmask_b32_e64 v3, v3, v4, s[40:41]
	v_cndmask_b32_e32 v4, 0, v183, vcc
	v_sub_f32_e32 v4, v3, v4
	v_min_f32_e32 v3, 0, v0
	v_mul_f32_e64 v0, |v0|, s3
	v_exp_f32_e32 v0, v0
	s_nop 0
	v_add_f32_e32 v0, 1.0, v0
	v_cmp_gt_f32_e32 vcc, s60, v0
	s_nop 1
	v_cndmask_b32_e64 v5, 0, 32, vcc
	v_ldexp_f32 v0, v0, v5
	v_log_f32_e32 v0, v0
	s_nop 0
	v_mul_f32_e32 v5, 0x3f317217, v0
	v_fma_f32 v5, v0, s4, -v5
	v_fmac_f32_e32 v5, 0x3377d1cf, v0
	v_fmac_f32_e32 v5, 0x3f317217, v0
	v_cmp_lt_f32_e64 s[40:41], |v0|, s5
	s_nop 1
	v_cndmask_b32_e64 v0, v0, v5, s[40:41]
	v_cndmask_b32_e32 v5, 0, v183, vcc
	v_sub_f32_e32 v5, v0, v5
	v_mul_f32_e64 v0, |v7|, s3
	v_exp_f32_e32 v0, v0
	v_pk_add_f32 v[2:3], v[2:3], v[4:5] neg_lo:[0,1] neg_hi:[0,1]
	v_mul_f32_e64 v5, |v8|, s3
	v_pk_mul_f32 v[2:3], v[2:3], s[6:7] op_sel_hi:[1,0]
	v_add_f32_e32 v0, 1.0, v0
	v_cmp_gt_f32_e32 vcc, s60, v0
	ds_write2_b32 v9, v2, v3 offset1:1
	v_exp_f32_e32 v5, v5
	v_cndmask_b32_e64 v3, 0, 32, vcc
	v_ldexp_f32 v0, v0, v3
	v_log_f32_e32 v0, v0
	v_add_f32_e32 v5, 1.0, v5
	v_min_f32_e32 v2, 0, v7
	v_readlane_b32 s3, v255, 21
	v_mul_f32_e32 v3, 0x3f317217, v0
	v_fma_f32 v3, v0, s4, -v3
	v_fmac_f32_e32 v3, 0x3377d1cf, v0
	v_fmac_f32_e32 v3, 0x3f317217, v0
	v_cmp_lt_f32_e64 s[40:41], |v0|, s5
	s_nop 1
	v_cndmask_b32_e64 v0, v0, v3, s[40:41]
	v_cndmask_b32_e32 v3, 0, v183, vcc
	v_cmp_gt_f32_e32 vcc, s60, v5
	v_sub_f32_e32 v4, v0, v3
	v_min_f32_e32 v3, 0, v8
	v_cndmask_b32_e64 v6, 0, 32, vcc
	v_ldexp_f32 v5, v5, v6
	v_log_f32_e32 v5, v5
	v_add_u32_e32 v0, 0xc808, v12
	v_mul_f32_e32 v6, 0x3f317217, v5
	v_fma_f32 v6, v5, s4, -v6
	v_fmac_f32_e32 v6, 0x3377d1cf, v5
	v_fmac_f32_e32 v6, 0x3f317217, v5
	v_cmp_lt_f32_e64 s[40:41], |v5|, s5
	s_nop 1
	v_cndmask_b32_e64 v5, v5, v6, s[40:41]
	v_cndmask_b32_e32 v6, 0, v183, vcc
	v_sub_f32_e32 v5, v5, v6
	v_pk_add_f32 v[2:3], v[2:3], v[4:5] neg_lo:[0,1] neg_hi:[0,1]
	s_nop 0
	v_pk_mul_f32 v[2:3], v[2:3], s[6:7] op_sel_hi:[1,0]
	ds_write2_b32 v0, v2, v3 offset1:1
	v_and_b32_e32 v0, 63, v11
	v_and_b32_e32 v2, 0x3ffffffc, v10
	v_mad_u32_u24 v6, v0, s86, 0
	v_lshl_add_u32 v8, v2, 2, v6
	v_add_u32_e32 v3, 0xfc, v13
	v_add_u32_e32 v9, 0xa700, v8
	s_waitcnt lgkmcnt(0)
	s_barrier
; DI void gla_load(const bf16_t* P, const float* wa2  , const float* ba  , float* L, int cid, int hh) {
;     ...
;     {
;         const int lane = tid & 63, wv = tid >> 6;
; #pragma unroll
;         for (int c = 0; c < 4; ++c) {
;             const int d = wv * 4 + c;
;             float vf = L[GL_BF + lane * 33 + d], vb = L[GL_BB + lane * 33 + d];
; #pragma unroll
;             for (int off = 1; off < 64; off <<= 1) {
;                 const float tf = __int_as_float(__builtin_amdgcn_ds_bpermute(((lane - off) & 63) << 2, __float_as_int(vf)));
;                 const float tb = __int_as_float(__builtin_amdgcn_ds_bpermute(((lane + off) & 63) << 2, __float_as_int(vb)));
;                 vf += (lane >= off) ? tf : 0.f;
;                 vb += (lane + off < 64) ? tb : 0.f;
;             }
;             L[GL_BF + lane * 33 + d] = vf; L[GL_BB + lane * 33 + d] = vb;
;         }
;     }
;     __syncthreads();
	v_and_b32_e32 v7, 0xfc, v3
	ds_read2_b32 v[2:3], v9 offset1:1
	v_add_u32_e32 v11, 0xc800, v8
	ds_read2_b32 v[4:5], v11 offset1:1
	v_lshlrev_b32_e32 v14, 2, v0
	v_add_u32_e32 v15, 4, v14
	s_waitcnt lgkmcnt(1)
	ds_bpermute_b32 v12, v7, v2
	v_and_b32_e32 v15, 0xfc, v15
	s_waitcnt lgkmcnt(1)
	ds_bpermute_b32 v16, v15, v4
	v_cmp_eq_u32_e64 s[56:57], 0, v0
	v_cmp_eq_u32_e64 s[58:59], 63, v0
	v_add_u32_e32 v17, 8, v14
	s_waitcnt lgkmcnt(1)
	v_cndmask_b32_e64 v12, v12, 0, s[56:57]
	v_add_f32_e32 v2, v2, v12
	s_waitcnt lgkmcnt(0)
	v_cndmask_b32_e64 v12, v16, 0, s[58:59]
	v_add_f32_e32 v4, v4, v12
	v_add_u32_e32 v12, 0xf8, v13
	v_and_b32_e32 v12, 0xfc, v12
	ds_bpermute_b32 v16, v12, v2
	v_and_b32_e32 v17, 0xfc, v17
	ds_bpermute_b32 v18, v17, v4
	v_cmp_gt_u32_e64 s[52:53], 2, v0
	v_cmp_gt_u32_e64 s[54:55], 62, v0
	v_add_u32_e32 v19, 16, v14
	s_waitcnt lgkmcnt(1)
	v_cndmask_b32_e64 v16, v16, 0, s[52:53]
	v_add_f32_e32 v2, v2, v16
	s_waitcnt lgkmcnt(0)
	v_cndmask_b32_e64 v16, 0, v18, s[54:55]
	v_add_f32_e32 v4, v4, v16
	v_add_u32_e32 v16, 0xf0, v13
	v_and_b32_e32 v16, 0xfc, v16
	ds_bpermute_b32 v18, v16, v2
	v_and_b32_e32 v19, 0xfc, v19
	ds_bpermute_b32 v20, v19, v4
	v_cmp_gt_u32_e64 s[48:49], 4, v0
	v_cmp_gt_u32_e64 s[50:51], 60, v0
	v_add_u32_e32 v21, 32, v14
	s_waitcnt lgkmcnt(1)
	v_cndmask_b32_e64 v18, v18, 0, s[48:49]
	v_add_f32_e32 v2, v2, v18
	s_waitcnt lgkmcnt(0)
	v_cndmask_b32_e64 v18, 0, v20, s[50:51]
	v_add_f32_e32 v4, v4, v18
	v_add_u32_e32 v18, 0xe0, v13
	v_and_b32_e32 v18, 0xfc, v18
	ds_bpermute_b32 v20, v18, v2
	v_and_b32_e32 v21, 0xfc, v21
	ds_bpermute_b32 v22, v21, v4
	v_cmp_gt_u32_e64 s[44:45], 8, v0
	v_cmp_gt_u32_e64 s[46:47], 56, v0
	v_add_u32_e32 v23, 64, v14
	s_waitcnt lgkmcnt(1)
	v_cndmask_b32_e64 v20, v20, 0, s[44:45]
	v_add_f32_e32 v2, v2, v20
	s_waitcnt lgkmcnt(0)
	v_cndmask_b32_e64 v20, 0, v22, s[46:47]
	v_add_f32_e32 v4, v4, v20
	v_add_u32_e32 v20, 0xc0, v13
	v_and_b32_e32 v20, 0xfc, v20
	ds_bpermute_b32 v22, v20, v2
	v_and_b32_e32 v23, 0xfc, v23
	ds_bpermute_b32 v24, v23, v4
	v_cmp_gt_u32_e64 s[40:41], 16, v0
	v_cmp_gt_u32_e64 s[42:43], 48, v0
	v_bitop3_b32 v13, v13, s80, v178 bitop3:0x6c
	s_waitcnt lgkmcnt(1)
	v_cndmask_b32_e64 v22, v22, 0, s[40:41]
	v_add_f32_e32 v2, v2, v22
	s_waitcnt lgkmcnt(0)
	v_cndmask_b32_e64 v22, 0, v24, s[42:43]
	v_add_f32_e32 v4, v4, v22
	ds_bpermute_b32 v22, v13, v2
	v_xor_b32_e32 v14, 0x80, v14
	ds_bpermute_b32 v24, v14, v4
	v_cmp_gt_u32_e32 vcc, 32, v0
	s_waitcnt lgkmcnt(1)
	s_nop 0
	v_cndmask_b32_e64 v0, v22, 0, vcc
	v_add_f32_e32 v0, v2, v0
	s_waitcnt lgkmcnt(0)
	v_cndmask_b32_e32 v2, 0, v24, vcc
	v_add_f32_e32 v2, v4, v2
	ds_bpermute_b32 v4, v7, v3
	ds_bpermute_b32 v22, v15, v5
	s_waitcnt lgkmcnt(1)
	v_cndmask_b32_e64 v4, v4, 0, s[56:57]
	v_add_f32_e32 v3, v3, v4
	s_waitcnt lgkmcnt(0)
	v_cndmask_b32_e64 v4, v22, 0, s[58:59]
	v_add_f32_e32 v4, v5, v4
	ds_bpermute_b32 v5, v12, v3
	ds_bpermute_b32 v22, v17, v4
	s_waitcnt lgkmcnt(1)
	v_cndmask_b32_e64 v5, v5, 0, s[52:53]
	v_add_f32_e32 v3, v3, v5
	s_waitcnt lgkmcnt(0)
	v_cndmask_b32_e64 v5, 0, v22, s[54:55]
	v_add_f32_e32 v4, v4, v5
	ds_bpermute_b32 v5, v16, v3
	ds_bpermute_b32 v22, v19, v4
	s_waitcnt lgkmcnt(1)
	v_cndmask_b32_e64 v5, v5, 0, s[48:49]
	v_add_f32_e32 v3, v3, v5
	s_waitcnt lgkmcnt(0)
	v_cndmask_b32_e64 v5, 0, v22, s[50:51]
	v_add_f32_e32 v4, v4, v5
	ds_bpermute_b32 v5, v18, v3
	ds_bpermute_b32 v22, v21, v4
	s_waitcnt lgkmcnt(1)
	v_cndmask_b32_e64 v5, v5, 0, s[44:45]
	v_add_f32_e32 v3, v3, v5
	s_waitcnt lgkmcnt(0)
	v_cndmask_b32_e64 v5, 0, v22, s[46:47]
	v_add_f32_e32 v4, v4, v5
	ds_bpermute_b32 v5, v20, v3
	ds_bpermute_b32 v22, v23, v4
	s_waitcnt lgkmcnt(1)
	v_cndmask_b32_e64 v5, v5, 0, s[40:41]
	v_add_f32_e32 v3, v3, v5
	s_waitcnt lgkmcnt(0)
	v_cndmask_b32_e64 v5, 0, v22, s[42:43]
	v_add_f32_e32 v4, v4, v5
	ds_bpermute_b32 v5, v13, v3
	ds_bpermute_b32 v22, v14, v4
	s_waitcnt lgkmcnt(1)
	v_cndmask_b32_e64 v5, v5, 0, vcc
	v_add_f32_e32 v3, v3, v5
	s_waitcnt lgkmcnt(0)
	v_cndmask_b32_e32 v5, 0, v22, vcc
	v_add_f32_e32 v4, v4, v5
	ds_write2_b32 v9, v0, v3 offset1:1
	ds_write2_b32 v11, v2, v4 offset1:1
	v_add_u32_e32 v0, 8, v8
	ds_read2st64_b32 v[2:3], v0 offset0:167 offset1:200
	s_waitcnt lgkmcnt(0)
	ds_bpermute_b32 v4, v7, v2
	ds_bpermute_b32 v5, v15, v3
	s_waitcnt lgkmcnt(1)
	v_cndmask_b32_e64 v4, v4, 0, s[56:57]
	v_add_f32_e32 v2, v2, v4
	s_waitcnt lgkmcnt(0)
	v_cndmask_b32_e64 v4, v5, 0, s[58:59]
	v_add_f32_e32 v3, v3, v4
	ds_bpermute_b32 v4, v12, v2
	ds_bpermute_b32 v5, v17, v3
	s_waitcnt lgkmcnt(1)
	v_cndmask_b32_e64 v4, v4, 0, s[52:53]
	v_add_f32_e32 v2, v2, v4
	s_waitcnt lgkmcnt(0)
	v_cndmask_b32_e64 v4, 0, v5, s[54:55]
	v_add_f32_e32 v3, v3, v4
	ds_bpermute_b32 v4, v16, v2
	ds_bpermute_b32 v5, v19, v3
	s_waitcnt lgkmcnt(1)
	v_cndmask_b32_e64 v4, v4, 0, s[48:49]
	v_add_f32_e32 v2, v2, v4
	s_waitcnt lgkmcnt(0)
	v_cndmask_b32_e64 v4, 0, v5, s[50:51]
	v_add_f32_e32 v3, v3, v4
	ds_bpermute_b32 v4, v18, v2
	ds_bpermute_b32 v5, v21, v3
	s_waitcnt lgkmcnt(1)
	v_cndmask_b32_e64 v4, v4, 0, s[44:45]
	v_add_f32_e32 v2, v2, v4
	s_waitcnt lgkmcnt(0)
	v_cndmask_b32_e64 v4, 0, v5, s[46:47]
	v_add_f32_e32 v3, v3, v4
	ds_bpermute_b32 v4, v20, v2
	ds_bpermute_b32 v5, v23, v3
	s_waitcnt lgkmcnt(1)
	v_cndmask_b32_e64 v4, v4, 0, s[40:41]
	v_add_f32_e32 v2, v2, v4
	s_waitcnt lgkmcnt(0)
	v_cndmask_b32_e64 v4, 0, v5, s[42:43]
	v_add_f32_e32 v3, v3, v4
	ds_bpermute_b32 v4, v13, v2
	ds_bpermute_b32 v5, v14, v3
	s_waitcnt lgkmcnt(1)
	v_cndmask_b32_e64 v4, v4, 0, vcc
	v_add_f32_e32 v2, v2, v4
	s_waitcnt lgkmcnt(0)
	v_cndmask_b32_e32 v4, 0, v5, vcc
	v_add_f32_e32 v3, v3, v4
	ds_write2st64_b32 v0, v2, v3 offset0:167 offset1:200
	v_lshl_or_b32 v0, v10, 2, 12
	v_add_u32_e32 v0, v6, v0
	ds_read2st64_b32 v[2:3], v0 offset0:167 offset1:200
	s_waitcnt lgkmcnt(0)
; #define LAS __attribute__((address_space(3)))
; DI unsigned pk_bf16(float lo, float hi) { unsigned r; asm("v_cvt_pk_bf16_f32 %0, %1, %2" : "=v"(r) : "v"(lo), "v"(hi)); return r; }
; DI void gla_pass1_item(unsigned char* ws, const float* wa2, const float* gba, unsigned char* lds, int cid, int hh) {
;     ...
;     {
;         float* GB = (float*)(ws + WS_M2) + (size_t)NCH * 4 * 2 * 2048 + ((size_t)cid * 4 + hh) * 4096;
;         const int r = tid >> 3, d0 = (tid & 7) * 4;
;         *(f32x4*)(GB + r * 32 + d0) = (f32x4){L[GL_BF + r * 33 + d0], L[GL_BF + r * 33 + d0 + 1], L[GL_BF + r * 33 + d0 + 2], L[GL_BF + r * 33 + d0 + 3]};
;         *(f32x4*)(GB + 2048 + r * 32 + d0) = (f32x4){L[GL_BB + r * 33 + d0], L[GL_BB + r * 33 + d0 + 1], L[GL_BB + r * 33 + d0 + 2], L[GL_BB + r * 33 + d0 + 3]};
;     }
;     bf16_t* KD = (bf16_t*)(lds + G3_QT);
;     bf16_t* VB = (bf16_t*)(lds + G3_VT);
;     {
;         const int c = tid >> 3, d0 = (tid & 7) * 4;
;         float kf[4], kb[4];
; #pragma unroll
;         for (int j = 0; j < 4; ++j) {
;             const float k = L[GL_K + c * 33 + d0 + j];
;             kf[j] = k * __expf(L[GL_BF + 63 * 33 + d0 + j] - L[GL_BF + c * 33 + d0 + j]);
;             kb[j] = k * __expf(L[GL_BB + 0 * 33 + d0 + j] - L[GL_BB + c * 33 + d0 + j]);
;         }
;         u32x2 o;
;         o[0] = pk_bf16(kf[0], kf[1]); o[1] = pk_bf16(kf[2], kf[3]); *(u32x2*)(KD + c * 40 + d0) = o;
;         o[0] = pk_bf16(kb[0], kb[1]); o[1] = pk_bf16(kb[2], kb[3]); *(u32x2*)(KD + 64 * 40 + c * 40 + d0) = o;
;     }
;     __syncthreads();
;     const size_t idx = ((size_t)cid * 4 + hh) * 2;
;     {
;         const int lane = tid & 63, fr = lane & 15, fq = lane >> 4, wv = tid >> 6, dir = wv >> 2, et = wv & 3;
;         const bf16_t* KDd = KD + dir * 64 * 40;
;         f32x4 a0 = (f32x4){0.f, 0.f, 0.f, 0.f}, a1 = a0;
; #pragma unroll
;         for (int ks = 0; ks < 2; ++ks) {
;             const int trr = ks * 32 + fq * 8 + (fr >> 2), trc = 4 * (fr & 3);
;             const s16x4 v0 = __builtin_amdgcn_ds_read_tr16_b64_v4i16((LAS s16x4*)(VB + trr * 72 + et * 16 + trc)), v1 = __builtin_amdgcn_ds_read_tr16_b64_v4i16((LAS s16x4*)(VB + (trr + 4) * 72 + et * 16 + trc));
;             const s16x4 k00 = __builtin_amdgcn_ds_read_tr16_b64_v4i16((LAS s16x4*)(KDd + trr * 40 + trc)), k01 = __builtin_amdgcn_ds_read_tr16_b64_v4i16((LAS s16x4*)(KDd + (trr + 4) * 40 + trc));
	ds_bpermute_b32 v4, v7, v2
	ds_bpermute_b32 v5, v15, v3
	s_waitcnt lgkmcnt(1)
	v_cndmask_b32_e64 v4, v4, 0, s[56:57]
	v_add_f32_e32 v2, v2, v4
	s_waitcnt lgkmcnt(0)
	v_cndmask_b32_e64 v4, v5, 0, s[58:59]
	v_add_f32_e32 v3, v3, v4
	ds_bpermute_b32 v4, v12, v2
	ds_bpermute_b32 v5, v17, v3
	s_waitcnt lgkmcnt(1)
	v_cndmask_b32_e64 v4, v4, 0, s[52:53]
	v_add_f32_e32 v2, v2, v4
	s_waitcnt lgkmcnt(0)
	v_cndmask_b32_e64 v4, 0, v5, s[54:55]
	v_add_f32_e32 v3, v3, v4
	ds_bpermute_b32 v4, v16, v2
	ds_bpermute_b32 v5, v19, v3
	s_waitcnt lgkmcnt(1)
	v_cndmask_b32_e64 v4, v4, 0, s[48:49]
	v_add_f32_e32 v2, v2, v4
	s_waitcnt lgkmcnt(0)
	v_cndmask_b32_e64 v4, 0, v5, s[50:51]
	v_add_f32_e32 v3, v3, v4
	ds_bpermute_b32 v4, v18, v2
	ds_bpermute_b32 v5, v21, v3
	s_waitcnt lgkmcnt(1)
	v_cndmask_b32_e64 v4, v4, 0, s[44:45]
	v_add_f32_e32 v2, v2, v4
	s_waitcnt lgkmcnt(0)
	v_cndmask_b32_e64 v4, 0, v5, s[46:47]
	v_add_f32_e32 v3, v3, v4
	ds_bpermute_b32 v4, v20, v2
	ds_bpermute_b32 v5, v23, v3
	s_waitcnt lgkmcnt(1)
	v_cndmask_b32_e64 v4, v4, 0, s[40:41]
	v_add_f32_e32 v2, v2, v4
	s_waitcnt lgkmcnt(0)
	v_cndmask_b32_e64 v4, 0, v5, s[42:43]
	v_add_f32_e32 v3, v3, v4
	ds_bpermute_b32 v4, v13, v2
	ds_bpermute_b32 v5, v14, v3
	s_lshl_b64 s[40:41], s[18:19], 14
	s_add_u32 s2, s2, s40
	s_addc_u32 s3, s3, s41
	s_waitcnt lgkmcnt(1)
	v_cndmask_b32_e64 v4, v4, 0, vcc
	v_add_f32_e32 v2, v2, v4
	s_waitcnt lgkmcnt(0)
	v_cndmask_b32_e32 v4, 0, v5, vcc
	v_add_f32_e32 v3, v3, v4
	ds_write2st64_b32 v0, v2, v3 offset0:167 offset1:200
	v_mov_b32_e32 v2, v176
	s_waitcnt lgkmcnt(0)
	s_barrier
	s_nop 0
	v_lshlrev_b32_e32 v0, 2, v2
	v_and_b32_e32 v16, 28, v0
	v_ashrrev_i32_e32 v3, 3, v2
	v_lshlrev_b32_e32 v0, 2, v16
	v_add_u32_e32 v17, 0, v0
	v_mul_lo_u32 v10, v3, s86
	v_add_u32_e32 v11, v17, v10
	v_add_u32_e32 v12, 0xa700, v11
	v_add_u32_e32 v18, 0xa708, v11
	ds_read2_b32 v[4:5], v12 offset1:1
	ds_read2_b32 v[6:7], v18 offset1:1
	v_lshlrev_b32_e32 v8, 5, v3
	v_ashrrev_i32_e32 v9, 31, v8
	v_lshl_add_u64 v[8:9], v[8:9], 2, s[2:3]
	v_lshl_add_u64 v[8:9], v[8:9], 0, v[0:1]
	s_waitcnt lgkmcnt(0)
	flat_store_dwordx4 v[8:9], v[4:7]
	v_add_u32_e32 v14, 0xc800, v11
	v_add_u32_e32 v19, 0xc808, v11
	ds_read2_b32 v[4:5], v14 offset1:1
	ds_read2_b32 v[6:7], v19 offset1:1
	v_add_co_u32_e32 v8, vcc, s61, v8
	v_add_u32_e32 v20, 0, v10
	s_nop 0
	v_addc_co_u32_e32 v9, vcc, 0, v9, vcc
	v_add_u32_e32 v0, v20, v0
	s_waitcnt lgkmcnt(0)
	flat_store_dwordx4 v[8:9], v[4:7]
	s_movk_i32 s2, 0xffcc
	v_bfe_u32 v26, v2, 4, 2
	v_add_u32_e32 v4, 0x2100, v0
	v_add_u32_e32 v5, 0xc77c, v17
	ds_read2_b32 v[8:9], v4 offset1:1
	ds_read2_b32 v[10:11], v5 offset1:1
	ds_read2_b32 v[12:13], v12 offset1:1
	v_add_u32_e32 v0, 0x2108, v0
	v_ashrrev_i32_e32 v24, 8, v2
	v_ashrrev_i32_e32 v25, 31, v24
	s_waitcnt lgkmcnt(0)
	v_sub_f32_e32 v4, v10, v12
	v_mul_f32_e32 v4, 0x3fb8aa3b, v4
	v_exp_f32_e32 v4, v4
	s_nop 0
	v_mul_f32_e32 v21, v8, v4
	ds_read_b128 v[4:7], v17 offset:51200
	ds_read2_b32 v[14:15], v14 offset1:1
	s_waitcnt lgkmcnt(0)
	v_sub_f32_e32 v4, v4, v14
	v_mul_f32_e32 v4, 0x3fb8aa3b, v4
	v_exp_f32_e32 v4, v4
	s_nop 0
	v_mul_f32_e32 v14, v8, v4
	v_sub_f32_e32 v4, v11, v13
	v_mul_f32_e32 v4, 0x3fb8aa3b, v4
	v_exp_f32_e32 v4, v4
	s_nop 0
	v_mul_f32_e32 v22, v9, v4
	v_sub_f32_e32 v4, v5, v15
	v_mul_f32_e32 v4, 0x3fb8aa3b, v4
	v_exp_f32_e32 v4, v4
	s_nop 0
	v_mul_f32_e32 v15, v9, v4
	ds_read2_b32 v[4:5], v0 offset1:1
	v_add_u32_e32 v0, 0xc784, v17
	ds_read2_b32 v[8:9], v0 offset1:1
	ds_read2_b32 v[10:11], v18 offset1:1
	ds_read2_b32 v[12:13], v19 offset1:1
	s_waitcnt lgkmcnt(0)
	v_sub_f32_e32 v0, v8, v10
	v_sub_f32_e32 v6, v6, v12
	v_mul_f32_e32 v0, 0x3fb8aa3b, v0
	v_mul_f32_e32 v6, 0x3fb8aa3b, v6
	v_exp_f32_e32 v0, v0
	v_exp_f32_e32 v6, v6
	v_mul_f32_e32 v0, v4, v0
	v_mul_f32_e32 v8, v4, v6
	v_sub_f32_e32 v4, v9, v11
	v_mul_f32_e32 v4, 0x3fb8aa3b, v4
	v_exp_f32_e32 v4, v4
	s_nop 0
	v_mul_f32_e32 v6, v5, v4
	v_sub_f32_e32 v4, v7, v13
	v_mul_f32_e32 v4, 0x3fb8aa3b, v4
	v_exp_f32_e32 v4, v4
	s_nop 0
	v_mul_f32_e32 v7, v5, v4
	v_cvt_pk_bf16_f32 v5, v0, v6
	v_mul_lo_u32 v0, v3, s2
	v_lshlrev_b32_e32 v3, 1, v16
	v_add3_u32 v0, v20, v0, v3
	v_cvt_pk_bf16_f32 v4, v21, v22
	v_add_u32_e32 v0, 0x100, v0
	v_cvt_pk_bf16_f32 v6, v14, v15
	v_cvt_pk_bf16_f32 v7, v8, v7
	ds_write2st64_b64 v0, v[4:5], v[6:7] offset0:116 offset1:126
	v_bfe_u32 v4, v2, 2, 2
	v_lshl_or_b32 v8, v26, 3, v4
	v_lshrrev_b32_e32 v4, 2, v2
	s_movk_i32 s2, 0x1400
	v_and_b32_e32 v27, 48, v4
	v_lshlrev_b32_e32 v5, 3, v2
	v_mad_i32_i24 v0, v24, s2, 0
	v_lshl_add_u32 v4, v27, 1, s69
	v_and_b32_e32 v9, 24, v5
	v_mul_u32_u24_e32 v5, 0x90, v8
	v_mul_u32_u24_e32 v8, 0x50, v8
	v_add3_u32 v16, v4, v9, v5
	v_add3_u32 v0, v0, v8, v9
	s_waitcnt lgkmcnt(0)
	s_barrier
	ds_read_b64_tr_b16 v[4:5], v16
	ds_read_b64_tr_b16 v[6:7], v16 offset:576
	ds_read_b64_tr_b16 v[10:11], v0 offset:59968
	ds_read_b64_tr_b16 v[8:9], v0 offset:59648
	ds_read_b64_tr_b16 v[12:13], v0 offset:59680
	ds_read_b64_tr_b16 v[14:15], v0 offset:60000
	s_waitcnt lgkmcnt(0)
	v_mfma_f32_16x16x32_bf16 v[8:11], v[4:7], v[8:11], 0
	v_readlane_b32 s2, v255, 9
	v_readlane_b32 s3, v255, 10
	s_add_u32 s2, s2, s40
	v_mfma_f32_16x16x32_bf16 v[4:7], v[4:7], v[12:15], 0
	ds_read_b64_tr_b16 v[12:13], v16 offset:4608
	ds_read_b64_tr_b16 v[14:15], v16 offset:5184
	ds_read_b64_tr_b16 v[16:17], v0 offset:62208
	ds_read_b64_tr_b16 v[18:19], v0 offset:62528
	ds_read_b64_tr_b16 v[20:21], v0 offset:62240
	ds_read_b64_tr_b16 v[22:23], v0 offset:62560
	s_addc_u32 s3, s3, s41
	v_lshlrev_b32_e32 v0, 2, v27
	s_waitcnt lgkmcnt(0)
	v_mfma_f32_16x16x32_bf16 v[8:11], v[12:15], v[16:19], v[8:11]
	v_and_b32_e32 v3, 15, v2
	v_mfma_f32_16x16x32_bf16 v[4:7], v[12:15], v[20:23], v[4:7]
	v_lshlrev_b64 v[12:13], 13, v[24:25]
	v_lshl_add_u64 v[12:13], s[2:3], 0, v[12:13]
	v_lshl_add_u64 v[12:13], v[12:13], 0, v[0:1]
	v_lshlrev_b32_e32 v0, 4, v26
	v_lshl_add_u64 v[12:13], v[12:13], 0, v[0:1]
	v_lshlrev_b32_e32 v0, 8, v3
	v_lshl_add_u64 v[12:13], v[12:13], 0, v[0:1]
	flat_store_dwordx4 v[12:13], v[8:11]
	s_nop 1
	v_add_co_u32_e32 v8, vcc, 0x1000, v12
	s_nop 1
	v_addc_co_u32_e32 v9, vcc, 0, v13, vcc
	v_cmp_lt_i32_e32 vcc, 31, v2
	flat_store_dwordx4 v[8:9], v[4:7]
	s_and_saveexec_b64 s[2:3], vcc
	s_xor_b64 s[40:41], exec, s[2:3]
	s_cbranch_execz .LBB0_469
	v_cmp_gt_u32_e32 vcc, 64, v2
	s_and_saveexec_b64 s[20:21], vcc
	s_cbranch_execz .LBB0_468
	v_lshl_add_u32 v0, v2, 2, 0
	ds_read_b32 v0, v0 offset:51072
	s_lshl_b64 s[2:3], s[18:19], 8
	v_readlane_b32 s4, v255, 22
	s_add_u32 s2, s4, s2
	v_readlane_b32 s4, v255, 11
	s_waitcnt lgkmcnt(0)
	v_mul_f32_e32 v0, 0x3fb8aa3b, v0
	v_exp_f32_e32 v0, v0
	s_addc_u32 s3, s4, s3
	v_mov_b32_e32 v3, v1
	v_lshl_add_u64 v[2:3], v[2:3], 2, s[2:3]
	flat_store_dword v[2:3], v0
